# NSA input-projection GEMM epilogue (kind 4) rewritten as straight blocks for the q and row-major k/v column tiles
# speedup vs baseline: 1.0120x; 1.0082x over previous
; DI void st8bf(bf16_t* dst, f32x4 v0, f32x4 v1) { u32x4 w; w.x = pk2(v0[0], v0[1]); w.y = pk2(v0[2], v0[3]); w.z = pk2(v1[0], v1[1]); w.w = pk2(v1[2], v1[3]); *(u32x4*)dst = w; }
;     DI void st(int row, int col, f32x4 v0, f32x4 v1) const {
;     ...
;         case EK_NSAIN: {
;             if (col < 1024) { st8bf(d0 + (size_t)row * 1024 + col, v0 * 0.18033688011112042f, v1 * 0.18033688011112042f);   }
;             else if (col < 2560) {
;                 const int cc0 = col - 1024, ts = cc0 >> 8, cc = cc0 & 255, g = cc >> 6, dd = cc & 63, b = row >> 11, t = row & 2047;
;                 bf16_t* base = d1 + (size_t)ts * (16 * MiB);
;                 if (ts == 3 || ts == 5) { bf16_t* d = base + ((size_t)(b * 4 + g) * 64 + dd) * 2048 + t;
; #pragma unroll
;                     for (int e = 0; e < 4; ++e) { d[(size_t)e * 2048] = f2bf(v0[e]); d[(size_t)(e + 4) * 2048] = f2bf(v1[e]); } }
;                 else st8bf(base + ((size_t)(b * 4 + g) * 2048 + t) * 64 + dd, v0, v1);
.Lnsa_epi:
	s_cmp_lt_u32 s70, 4
	s_cbranch_scc1 .Lnsa_q
	s_cmp_eq_u32 s70, 7
	s_cbranch_scc1 .Lnsa_back
	s_cmp_gt_u32 s70, 8
	s_cbranch_scc1 .Lnsa_back
	s_sub_i32 s71, s70, 4
	s_lshl_b32 s71, s71, 25
	s_add_u32 s76, s14, s71
	s_addc_u32 s77, s15, 0
	s_lshr_b32 s71, s36, 3
	s_lshl_b32 s71, s71, 20
	s_and_b32 s80, s36, 7
	s_lshl_b32 s80, s80, 15
	s_add_u32 s71, s71, s80
	s_add_u32 s76, s76, s71
	s_addc_u32 s77, s77, 0
	v_lshrrev_b32_e32 v228, 6, v194
	v_lshlrev_b32_e32 v228, 18, v228
	v_lshl_add_u32 v228, v183, 7, v228
	v_and_b32_e32 v229, 63, v194
	v_lshl_add_u32 v228, v229, 1, v228
	v_add_u32_e32 v229, 0x80000, v228
	s_movk_i32 s81, 0x800
	s_movk_i32 s80, 0x2800
	v_cvt_pk_bf16_f32 v128, v124, v125
	v_cvt_pk_bf16_f32 v129, v126, v127
	v_cvt_pk_bf16_f32 v130, v120, v121
	v_cvt_pk_bf16_f32 v131, v122, v123
	global_store_dwordx4 v228, v[128:131], s[76:77]
	v_cvt_pk_bf16_f32 v132, v112, v113
	v_cvt_pk_bf16_f32 v133, v114, v115
	v_cvt_pk_bf16_f32 v134, v108, v109
	v_cvt_pk_bf16_f32 v135, v110, v111
	global_store_dwordx4 v229, v[132:135], s[76:77]
	s_add_u32 s76, s76, s81
	s_addc_u32 s77, s77, 0
	v_cvt_pk_bf16_f32 v136, v116, v117
	v_cvt_pk_bf16_f32 v137, v118, v119
	v_cvt_pk_bf16_f32 v138, v104, v105
	v_cvt_pk_bf16_f32 v139, v106, v107
	global_store_dwordx4 v228, v[136:139], s[76:77]
	v_cvt_pk_bf16_f32 v140, v96, v97
	v_cvt_pk_bf16_f32 v141, v98, v99
	v_cvt_pk_bf16_f32 v142, v92, v93
	v_cvt_pk_bf16_f32 v143, v94, v95
	global_store_dwordx4 v229, v[140:143], s[76:77]
	s_add_u32 s76, s76, s81
	s_addc_u32 s77, s77, 0
	v_cvt_pk_bf16_f32 v128, v100, v101
	v_cvt_pk_bf16_f32 v129, v102, v103
	v_cvt_pk_bf16_f32 v130, v88, v89
	v_cvt_pk_bf16_f32 v131, v90, v91
	global_store_dwordx4 v228, v[128:131], s[76:77]
	v_cvt_pk_bf16_f32 v132, v80, v81
	v_cvt_pk_bf16_f32 v133, v82, v83
	v_cvt_pk_bf16_f32 v134, v76, v77
	v_cvt_pk_bf16_f32 v135, v78, v79
	global_store_dwordx4 v229, v[132:135], s[76:77]
	s_add_u32 s76, s76, s81
	s_addc_u32 s77, s77, 0
	v_cvt_pk_bf16_f32 v136, v84, v85
	v_cvt_pk_bf16_f32 v137, v86, v87
	v_cvt_pk_bf16_f32 v138, v72, v73
	v_cvt_pk_bf16_f32 v139, v74, v75
	global_store_dwordx4 v228, v[136:139], s[76:77]
	v_cvt_pk_bf16_f32 v140, v68, v69
	v_cvt_pk_bf16_f32 v141, v70, v71
	v_cvt_pk_bf16_f32 v142, v64, v65
	v_cvt_pk_bf16_f32 v143, v66, v67
	global_store_dwordx4 v229, v[140:143], s[76:77]
	s_add_u32 s76, s76, s80
	s_addc_u32 s77, s77, 0
	v_cvt_pk_bf16_f32 v128, v60, v61
	v_cvt_pk_bf16_f32 v129, v62, v63
	v_cvt_pk_bf16_f32 v130, v56, v57
	v_cvt_pk_bf16_f32 v131, v58, v59
	global_store_dwordx4 v228, v[128:131], s[76:77]
	v_cvt_pk_bf16_f32 v132, v48, v49
	v_cvt_pk_bf16_f32 v133, v50, v51
	v_cvt_pk_bf16_f32 v134, v44, v45
	v_cvt_pk_bf16_f32 v135, v46, v47
	global_store_dwordx4 v229, v[132:135], s[76:77]
	s_add_u32 s76, s76, s81
	s_addc_u32 s77, s77, 0
	v_cvt_pk_bf16_f32 v136, v52, v53
	v_cvt_pk_bf16_f32 v137, v54, v55
	v_cvt_pk_bf16_f32 v138, v40, v41
	v_cvt_pk_bf16_f32 v139, v42, v43
	global_store_dwordx4 v228, v[136:139], s[76:77]
	v_cvt_pk_bf16_f32 v140, v24, v25
	v_cvt_pk_bf16_f32 v141, v26, v27
	v_cvt_pk_bf16_f32 v142, v20, v21
	v_cvt_pk_bf16_f32 v143, v22, v23
	global_store_dwordx4 v229, v[140:143], s[76:77]
	s_add_u32 s76, s76, s81
	s_addc_u32 s77, s77, 0
	v_cvt_pk_bf16_f32 v128, v36, v37
	v_cvt_pk_bf16_f32 v129, v38, v39
	v_cvt_pk_bf16_f32 v130, v16, v17
	v_cvt_pk_bf16_f32 v131, v18, v19
	global_store_dwordx4 v228, v[128:131], s[76:77]
	v_cvt_pk_bf16_f32 v132, v28, v29
	v_cvt_pk_bf16_f32 v133, v30, v31
	v_cvt_pk_bf16_f32 v134, v32, v33
	v_cvt_pk_bf16_f32 v135, v34, v35
	global_store_dwordx4 v229, v[132:135], s[76:77]
	s_add_u32 s76, s76, s81
	s_addc_u32 s77, s77, 0
	v_cvt_pk_bf16_f32 v136, v12, v13
	v_cvt_pk_bf16_f32 v137, v14, v15
	v_cvt_pk_bf16_f32 v138, v0, v1
	v_cvt_pk_bf16_f32 v139, v2, v3
	global_store_dwordx4 v228, v[136:139], s[76:77]
	v_cvt_pk_bf16_f32 v140, v8, v9
	v_cvt_pk_bf16_f32 v141, v10, v11
	v_cvt_pk_bf16_f32 v142, v4, v5
	v_cvt_pk_bf16_f32 v143, v6, v7
	global_store_dwordx4 v229, v[140:143], s[76:77]
	s_branch .Lnsa_done
; DI void st8bf(bf16_t* dst, f32x4 v0, f32x4 v1) { u32x4 w; w.x = pk2(v0[0], v0[1]); w.y = pk2(v0[2], v0[3]); w.z = pk2(v1[0], v1[1]); w.w = pk2(v1[2], v1[3]); *(u32x4*)dst = w; }
;     DI void st(int row, int col, f32x4 v0, f32x4 v1) const {
;     ...
;         case EK_ABIN: {
;             if (col < 256) st8bf(d0 + (size_t)row * 256 + col, v0, v1);
;             else if (col < 2560) st8bf(d1 + (size_t)row * 2304 + (col - 256), v0, v1);
;             else if (col < 3328) st8bf(d2 + (size_t)row * 768 + (col - 2560), v0, v1);
;     ...
;         case EK_NSAIN: {
;             if (col < 1024) { st8bf(d0 + (size_t)row * 1024 + col, v0 * 0.18033688011112042f, v1 * 0.18033688011112042f);   }
.Lnsa_q:
	s_lshl_b32 s71, s36, 19
	s_lshl_b32 s80, s70, 9
	s_add_u32 s71, s71, s80
	s_add_u32 s76, s12, s71
	s_addc_u32 s77, s13, 0
	v_lshlrev_b32_e32 v229, 1, v194
	v_lshl_add_u32 v228, v183, 11, v229
	s_mov_b32 s98, 0x3e38aa3b
	s_mov_b32 s99, 0x3e38aa3b
	s_mov_b32 s81, 0x8000
	s_mov_b32 s80, 0x28000
	v_pk_mul_f32 v[124:125], v[124:125], s[98:99]
	v_pk_mul_f32 v[126:127], v[126:127], s[98:99]
	v_pk_mul_f32 v[120:121], v[120:121], s[98:99]
	v_pk_mul_f32 v[122:123], v[122:123], s[98:99]
	v_cvt_pk_bf16_f32 v128, v124, v125
	v_cvt_pk_bf16_f32 v129, v126, v127
	v_cvt_pk_bf16_f32 v130, v120, v121
	v_cvt_pk_bf16_f32 v131, v122, v123
	global_store_dwordx4 v228, v[128:131], s[76:77]
	v_pk_mul_f32 v[112:113], v[112:113], s[98:99]
	v_pk_mul_f32 v[114:115], v[114:115], s[98:99]
	v_pk_mul_f32 v[108:109], v[108:109], s[98:99]
	v_pk_mul_f32 v[110:111], v[110:111], s[98:99]
	v_cvt_pk_bf16_f32 v132, v112, v113
	v_cvt_pk_bf16_f32 v133, v114, v115
	v_cvt_pk_bf16_f32 v134, v108, v109
	v_cvt_pk_bf16_f32 v135, v110, v111
	global_store_dwordx4 v228, v[132:135], s[76:77] offset:256
	s_add_u32 s76, s76, s81
	s_addc_u32 s77, s77, 0
	v_pk_mul_f32 v[116:117], v[116:117], s[98:99]
	v_pk_mul_f32 v[118:119], v[118:119], s[98:99]
	v_pk_mul_f32 v[104:105], v[104:105], s[98:99]
	v_pk_mul_f32 v[106:107], v[106:107], s[98:99]
	v_cvt_pk_bf16_f32 v136, v116, v117
	v_cvt_pk_bf16_f32 v137, v118, v119
	v_cvt_pk_bf16_f32 v138, v104, v105
	v_cvt_pk_bf16_f32 v139, v106, v107
	global_store_dwordx4 v228, v[136:139], s[76:77]
	v_pk_mul_f32 v[96:97], v[96:97], s[98:99]
	v_pk_mul_f32 v[98:99], v[98:99], s[98:99]
	v_pk_mul_f32 v[92:93], v[92:93], s[98:99]
	v_pk_mul_f32 v[94:95], v[94:95], s[98:99]
	v_cvt_pk_bf16_f32 v140, v96, v97
	v_cvt_pk_bf16_f32 v141, v98, v99
	v_cvt_pk_bf16_f32 v142, v92, v93
	v_cvt_pk_bf16_f32 v143, v94, v95
	global_store_dwordx4 v228, v[140:143], s[76:77] offset:256
	s_add_u32 s76, s76, s81
	s_addc_u32 s77, s77, 0
	v_pk_mul_f32 v[100:101], v[100:101], s[98:99]
	v_pk_mul_f32 v[102:103], v[102:103], s[98:99]
	v_pk_mul_f32 v[88:89], v[88:89], s[98:99]
	v_pk_mul_f32 v[90:91], v[90:91], s[98:99]
	v_cvt_pk_bf16_f32 v128, v100, v101
	v_cvt_pk_bf16_f32 v129, v102, v103
	v_cvt_pk_bf16_f32 v130, v88, v89
	v_cvt_pk_bf16_f32 v131, v90, v91
	global_store_dwordx4 v228, v[128:131], s[76:77]
	v_pk_mul_f32 v[80:81], v[80:81], s[98:99]
	v_pk_mul_f32 v[82:83], v[82:83], s[98:99]
	v_pk_mul_f32 v[76:77], v[76:77], s[98:99]
	v_pk_mul_f32 v[78:79], v[78:79], s[98:99]
	v_cvt_pk_bf16_f32 v132, v80, v81
	v_cvt_pk_bf16_f32 v133, v82, v83
	v_cvt_pk_bf16_f32 v134, v76, v77
	v_cvt_pk_bf16_f32 v135, v78, v79
	global_store_dwordx4 v228, v[132:135], s[76:77] offset:256
	s_add_u32 s76, s76, s81
	s_addc_u32 s77, s77, 0
	v_pk_mul_f32 v[84:85], v[84:85], s[98:99]
	v_pk_mul_f32 v[86:87], v[86:87], s[98:99]
	v_pk_mul_f32 v[72:73], v[72:73], s[98:99]
	v_pk_mul_f32 v[74:75], v[74:75], s[98:99]
	v_cvt_pk_bf16_f32 v136, v84, v85
	v_cvt_pk_bf16_f32 v137, v86, v87
	v_cvt_pk_bf16_f32 v138, v72, v73
	v_cvt_pk_bf16_f32 v139, v74, v75
	global_store_dwordx4 v228, v[136:139], s[76:77]
	v_pk_mul_f32 v[68:69], v[68:69], s[98:99]
	v_pk_mul_f32 v[70:71], v[70:71], s[98:99]
	v_pk_mul_f32 v[64:65], v[64:65], s[98:99]
	v_pk_mul_f32 v[66:67], v[66:67], s[98:99]
	v_cvt_pk_bf16_f32 v140, v68, v69
	v_cvt_pk_bf16_f32 v141, v70, v71
	v_cvt_pk_bf16_f32 v142, v64, v65
	v_cvt_pk_bf16_f32 v143, v66, v67
	global_store_dwordx4 v228, v[140:143], s[76:77] offset:256
	s_add_u32 s76, s76, s80
	s_addc_u32 s77, s77, 0
	v_pk_mul_f32 v[60:61], v[60:61], s[98:99]
	v_pk_mul_f32 v[62:63], v[62:63], s[98:99]
	v_pk_mul_f32 v[56:57], v[56:57], s[98:99]
	v_pk_mul_f32 v[58:59], v[58:59], s[98:99]
	v_cvt_pk_bf16_f32 v128, v60, v61
	v_cvt_pk_bf16_f32 v129, v62, v63
	v_cvt_pk_bf16_f32 v130, v56, v57
	v_cvt_pk_bf16_f32 v131, v58, v59
	global_store_dwordx4 v228, v[128:131], s[76:77]
	v_pk_mul_f32 v[48:49], v[48:49], s[98:99]
	v_pk_mul_f32 v[50:51], v[50:51], s[98:99]
	v_pk_mul_f32 v[44:45], v[44:45], s[98:99]
	v_pk_mul_f32 v[46:47], v[46:47], s[98:99]
	v_cvt_pk_bf16_f32 v132, v48, v49
	v_cvt_pk_bf16_f32 v133, v50, v51
	v_cvt_pk_bf16_f32 v134, v44, v45
	v_cvt_pk_bf16_f32 v135, v46, v47
	global_store_dwordx4 v228, v[132:135], s[76:77] offset:256
	s_add_u32 s76, s76, s81
	s_addc_u32 s77, s77, 0
	v_pk_mul_f32 v[52:53], v[52:53], s[98:99]
	v_pk_mul_f32 v[54:55], v[54:55], s[98:99]
	v_pk_mul_f32 v[40:41], v[40:41], s[98:99]
	v_pk_mul_f32 v[42:43], v[42:43], s[98:99]
	v_cvt_pk_bf16_f32 v136, v52, v53
	v_cvt_pk_bf16_f32 v137, v54, v55
	v_cvt_pk_bf16_f32 v138, v40, v41
	v_cvt_pk_bf16_f32 v139, v42, v43
	global_store_dwordx4 v228, v[136:139], s[76:77]
	v_pk_mul_f32 v[24:25], v[24:25], s[98:99]
	v_pk_mul_f32 v[26:27], v[26:27], s[98:99]
	v_pk_mul_f32 v[20:21], v[20:21], s[98:99]
	v_pk_mul_f32 v[22:23], v[22:23], s[98:99]
	v_cvt_pk_bf16_f32 v140, v24, v25
	v_cvt_pk_bf16_f32 v141, v26, v27
	v_cvt_pk_bf16_f32 v142, v20, v21
	v_cvt_pk_bf16_f32 v143, v22, v23
	global_store_dwordx4 v228, v[140:143], s[76:77] offset:256
	s_add_u32 s76, s76, s81
	s_addc_u32 s77, s77, 0
	v_pk_mul_f32 v[36:37], v[36:37], s[98:99]
	v_pk_mul_f32 v[38:39], v[38:39], s[98:99]
	v_pk_mul_f32 v[16:17], v[16:17], s[98:99]
	v_pk_mul_f32 v[18:19], v[18:19], s[98:99]
	v_cvt_pk_bf16_f32 v128, v36, v37
	v_cvt_pk_bf16_f32 v129, v38, v39
	v_cvt_pk_bf16_f32 v130, v16, v17
	v_cvt_pk_bf16_f32 v131, v18, v19
	global_store_dwordx4 v228, v[128:131], s[76:77]
	v_pk_mul_f32 v[28:29], v[28:29], s[98:99]
	v_pk_mul_f32 v[30:31], v[30:31], s[98:99]
	v_pk_mul_f32 v[32:33], v[32:33], s[98:99]
	v_pk_mul_f32 v[34:35], v[34:35], s[98:99]
	v_cvt_pk_bf16_f32 v132, v28, v29
	v_cvt_pk_bf16_f32 v133, v30, v31
	v_cvt_pk_bf16_f32 v134, v32, v33
	v_cvt_pk_bf16_f32 v135, v34, v35
	global_store_dwordx4 v228, v[132:135], s[76:77] offset:256
	s_add_u32 s76, s76, s81
	s_addc_u32 s77, s77, 0
	v_pk_mul_f32 v[12:13], v[12:13], s[98:99]
	v_pk_mul_f32 v[14:15], v[14:15], s[98:99]
	v_pk_mul_f32 v[0:1], v[0:1], s[98:99]
	v_pk_mul_f32 v[2:3], v[2:3], s[98:99]
	v_cvt_pk_bf16_f32 v136, v12, v13
	v_cvt_pk_bf16_f32 v137, v14, v15
	v_cvt_pk_bf16_f32 v138, v0, v1
	v_cvt_pk_bf16_f32 v139, v2, v3
	global_store_dwordx4 v228, v[136:139], s[76:77]
	v_pk_mul_f32 v[8:9], v[8:9], s[98:99]
	v_pk_mul_f32 v[10:11], v[10:11], s[98:99]
	v_pk_mul_f32 v[4:5], v[4:5], s[98:99]
	v_pk_mul_f32 v[6:7], v[6:7], s[98:99]
	v_cvt_pk_bf16_f32 v140, v8, v9
	v_cvt_pk_bf16_f32 v141, v10, v11
	v_cvt_pk_bf16_f32 v142, v4, v5
	v_cvt_pk_bf16_f32 v143, v6, v7
	global_store_dwordx4 v228, v[140:143], s[76:77] offset:256
.Lnsa_done:
	s_branch .LBB0_649
.Labin_epi:
	s_cmp_eq_u32 s70, 13
	s_cbranch_scc1 .Labin_back
	s_cmp_lt_u32 s70, 1
	s_cbranch_scc1 .Labin_c0
	s_cmp_lt_u32 s70, 10
	s_cbranch_scc1 .Labin_c1
	v_readlane_b32 s76, v254, 47
	v_readlane_b32 s77, v254, 48
	s_movk_i32 s80, 0x600
	s_sub_i32 s71, s70, 10
	s_branch .Labin_go

; template <class F>
; DI void gemm_phase(const int tid, LAS unsigned char* lds, const bf16_t* Ap, int lda, const bf16_t* Bp, int ldb, int M, int N, int K, int G, int c, bool direct, const F& E) {
;     ...
;         if (E.kind == 7  ) E.fused(acc, cur.pm, cur.pn, wr, wc, fr, fq);
;         else if (E.kind == 3  ) {
.Labin_back:
	s_cmp_eq_u32 s92, 4
	s_cbranch_scc1 .Lnsa_epi
